# v85 + nt on the four per-lane-contiguous r loads of gla_finalize so they bypass L1 and leave it to the O-plane lines that four waves share
# baseline (speedup 1.0000x reference)
; __device__ __forceinline__ unsigned pk2(float lo, float hi) { return f2bf(lo) | (f2bf(hi) << 16); }
; __device__ __forceinline__ float siluf_(float x) { return x * __builtin_amdgcn_rcpf(1.0f + __expf(-x)); }
; __device__ __forceinline__ void gla_finalize(const Ctx& F) {
;     ...
;     for (int row = gw; row < SEQ; row += NGW) {
;         f32x4 o[8]; const u32x4* op0 = (const u32x4*)(O + ((size_t)(lane * 2) * SEQ + row) * 16); const u32x4* op1 = (const u32x4*)(O + ((size_t)(lane * 2 + 1) * SEQ + row) * 16); float ss = 0.f;
;         const u32x4 ob[4] = {op0[0], op0[1], op1[0], op1[1]};
; #pragma unroll
;         for (int i = 0; i < 8; ++i) { const u32x4 q4 = ob[i >> 1]; const unsigned w0 = (i & 1) ? q4.z : q4.x, w1 = (i & 1) ? q4.w : q4.y;
;             o[i] = (f32x4){__uint_as_float(w0 << 16), __uint_as_float(w0 & 0xffff0000u), __uint_as_float(w1 << 16), __uint_as_float(w1 & 0xffff0000u)}; ss += (o[i][0] * o[i][0] + o[i][1] * o[i][1]) + (o[i][2] * o[i][2] + o[i][3] * o[i][3]); }
;         ss += __shfl_xor(ss, 1); ss += __shfl_xor(ss, 2); ss += __shfl_xor(ss, 4); ss += __shfl_xor(ss, 8);
;         const float rstd = rsqrtf(ss * (1.0f / 512.0f) + EPS);
;         const u32x4* rp = (const u32x4*)(Y1 + (size_t)row * 6144 + 4096 + lane * 32); u32x4* cp = (u32x4*)(CAT + (size_t)row * 2048 + lane * 32);
; #pragma unroll
;         for (int i = 0; i < 4; ++i) { const u32x4 rv = rp[i]; const unsigned rr[4] = {rv.x, rv.y, rv.z, rv.w}; unsigned ov[4];
; #pragma unroll
;             for (int j = 0; j < 4; ++j) { const int e = i * 8 + j * 2; const float r0 = __uint_as_float(rr[j] << 16), r1 = __uint_as_float(rr[j] & 0xffff0000u);
;                 const float x0 = o[e >> 2][e & 3], x1 = o[(e + 1) >> 2][(e + 1) & 3];
;                 ov[j] = pk2(x0 * rstd * P.in[36][d0 + e] * siluf_(r0), x1 * rstd * P.in[36][d0 + e + 1] * siluf_(r1)); }
.LBB0_1904:
	v_lshl_add_u64 v[20:21], s[92:93], 0, v[18:19]
	v_lshl_add_u64 v[8:9], s[92:93], 0, v[16:17]
	v_add_co_u32_e32 v54, vcc, 0xac00000, v20
	v_add_co_u32_e64 v58, s[0:1], s7, v8
	v_lshl_add_u64 v[10:11], s[92:93], 0, v[14:15]
	s_nop 0
	v_addc_co_u32_e64 v59, s[0:1], 0, v9, s[0:1]
	v_addc_co_u32_e32 v55, vcc, 0, v21, vcc
	v_lshl_add_u64 v[28:29], v[20:21], 0, s[16:17]
	v_lshl_add_u64 v[52:53], v[20:21], 0, s[18:19]
	v_add_co_u32_e64 v22, s[0:1], s23, v10
	v_add_co_u32_e32 v20, vcc, 0xac80000, v20
	v_mov_b32_e32 v0, v164
	v_mov_b32_e32 v1, v165
	v_mov_b32_e32 v2, v166
	v_mov_b32_e32 v3, v167
	v_mov_b32_e32 v4, v160
	v_mov_b32_e32 v5, v161
	v_mov_b32_e32 v6, v162
	v_mov_b32_e32 v7, v163
	v_lshl_add_u64 v[56:57], v[8:9], 0, s[20:21]
	v_addc_co_u32_e64 v23, s[0:1], 0, v11, s[0:1]
	global_load_dwordx4 v[24:27], v[28:29], off offset:16
	global_load_dwordx4 v[44:47], v[52:53], off offset:16
	global_load_dwordx4 v[30:33], v[58:59], off nt
	global_load_dwordx4 v[34:37], v[56:57], off offset:16 nt
	global_load_dwordx4 v[48:51], v[56:57], off offset:32 nt
	global_load_dwordx4 v[8:11], v[56:57], off offset:48 nt
	v_addc_co_u32_e32 v21, vcc, 0, v21, vcc
	global_load_dwordx4 v[52:55], v[54:55], off
	s_add_i32 s6, s6, s8
	global_load_dwordx4 v[56:59], v[20:21], off
	v_lshl_add_u64 v[14:15], v[14:15], 0, s[10:11]
	v_lshl_add_u64 v[16:17], v[16:17], 0, s[12:13]
	v_lshl_add_u64 v[18:19], v[18:19], 0, s[14:15]
	s_cmpk_lt_i32 s6, 0x4000
	s_waitcnt vmcnt(9)
	v_mov_b32_e32 v62, v0
	s_waitcnt vmcnt(8)
	v_mov_b32_e32 v60, v4
	s_waitcnt vmcnt(7)
	v_and_b32_e32 v70, 0xffff0000, v26
	s_waitcnt vmcnt(6)
	v_lshlrev_b32_e32 v4, 16, v44
	v_and_b32_e32 v0, 0xffff0000, v44
	v_lshlrev_b32_e32 v28, 16, v45
	s_waitcnt vmcnt(5)
	v_and_b32_e32 v75, 0xffff0000, v31
	v_lshlrev_b32_e32 v76, 16, v32
	v_lshlrev_b32_e32 v20, 16, v46
	s_waitcnt vmcnt(1)
	v_lshlrev_b32_e32 v93, 16, v53
	v_lshlrev_b32_e32 v92, 16, v52
	v_and_b32_e32 v53, 0xffff0000, v53
	v_and_b32_e32 v52, 0xffff0000, v52
	v_lshlrev_b32_e32 v95, 16, v55
	v_lshlrev_b32_e32 v94, 16, v54
	v_and_b32_e32 v55, 0xffff0000, v55
	v_and_b32_e32 v54, 0xffff0000, v54
	v_lshlrev_b32_e32 v65, 16, v25
	v_lshlrev_b32_e32 v64, 16, v24
	v_and_b32_e32 v67, 0xffff0000, v25
	v_and_b32_e32 v66, 0xffff0000, v24
	v_lshlrev_b32_e32 v68, 16, v26
	v_lshlrev_b32_e32 v72, 16, v27
	v_and_b32_e32 v29, 0xffff0000, v45
	v_lshlrev_b32_e32 v81, 16, v35
	v_lshlrev_b32_e32 v80, 16, v34
	v_and_b32_e32 v83, 0xffff0000, v35
	v_and_b32_e32 v82, 0xffff0000, v34
	v_lshlrev_b32_e32 v85, 16, v37
	v_lshlrev_b32_e32 v84, 16, v36
	v_and_b32_e32 v87, 0xffff0000, v37
	v_and_b32_e32 v86, 0xffff0000, v36
	v_lshlrev_b32_e32 v35, 16, v51
	v_lshlrev_b32_e32 v34, 16, v50
	v_and_b32_e32 v37, 0xffff0000, v51
	v_and_b32_e32 v36, 0xffff0000, v50
	v_lshlrev_b32_e32 v21, 16, v47
	v_and_b32_e32 v25, 0xffff0000, v47
	v_and_b32_e32 v24, 0xffff0000, v46
	v_mul_f32_e32 v51, v70, v70
	v_mul_f32_e32 v89, v4, v4
	v_mul_f32_e32 v91, v0, v0
	v_mul_f32_e32 v50, v28, v28
	v_mul_f32_e32 v104, 0xbfb8aa3b, v75
	v_mul_f32_e32 v112, 0xbfb8aa3b, v76
	v_mov_b32_e32 v88, v20
	v_mov_b32_e32 v90, v20
	s_waitcnt vmcnt(0)
	v_lshlrev_b32_e32 v101, 16, v59
	v_lshlrev_b32_e32 v100, 16, v58
	v_and_b32_e32 v59, 0xffff0000, v59
	v_and_b32_e32 v58, 0xffff0000, v58
	v_mov_b32_e32 v106, v52
	v_mov_b32_e32 v107, v54
	v_mov_b32_e32 v110, v53
	v_mov_b32_e32 v111, v55
	v_and_b32_e32 v73, 0xffff0000, v27
	v_lshlrev_b32_e32 v45, 16, v31
	v_lshlrev_b32_e32 v44, 16, v30
	v_and_b32_e32 v74, 0xffff0000, v30
	v_lshlrev_b32_e32 v77, 16, v33
	v_and_b32_e32 v79, 0xffff0000, v33
	v_and_b32_e32 v78, 0xffff0000, v32
	v_lshlrev_b32_e32 v31, 16, v49
	v_lshlrev_b32_e32 v30, 16, v48
	v_and_b32_e32 v33, 0xffff0000, v49
	v_and_b32_e32 v32, 0xffff0000, v48
	v_mul_f32_e32 v49, v68, v68
	v_mul_f32_e32 v48, v72, v72
	v_pk_mul_f32 v[96:97], v[24:25], v[24:25]
	v_pk_mul_f32 v[98:99], v[20:21], v[20:21]
	v_pk_fma_f32 v[102:103], v[28:29], v[28:29], v[50:51] op_sel_hi:[1,1,0]
	v_exp_f32_e32 v132, v104
	v_mov_b32_e32 v104, v92
	v_mov_b32_e32 v105, v94
	v_mov_b32_e32 v108, v93
	v_mov_b32_e32 v109, v95
	v_exp_f32_e32 v133, v112
	v_lshlrev_b32_e32 v112, 16, v56
	v_pk_add_f32 v[88:89], v[88:89], v[90:91]
	v_pk_mul_f32 v[90:91], v[58:59], v[58:59]
	v_pk_mul_f32 v[106:107], v[106:107], v[106:107]
	v_pk_mul_f32 v[110:111], v[110:111], v[110:111]
	v_mov_b32_e32 v69, v72
	v_mov_b32_e32 v71, v73
	v_pk_fma_f32 v[72:73], v[72:73], v[72:73], v[48:49] op_sel_hi:[1,1,0]
	v_mov_b32_e32 v48, v112
	v_mov_b32_e32 v50, v112
	v_mov_b32_e32 v88, v98
	v_mov_b32_e32 v102, v96
	v_pk_fma_f32 v[90:91], v[100:101], v[100:101], v[90:91]
	v_pk_fma_f32 v[104:105], v[104:105], v[104:105], v[106:107]
	v_pk_fma_f32 v[106:107], v[108:109], v[108:109], v[110:111]
	v_pk_mul_f32 v[46:47], v[66:67], v[66:67]
	v_mul_f32_e32 v113, 0xbfb8aa3b, v78
	v_pk_add_f32 v[48:49], v[48:49], v[50:51]
	v_pk_add_f32 v[50:51], v[88:89], v[102:103]
	v_pk_add_f32 v[88:89], v[90:91], v[90:91] op_sel_hi:[0,1]
	v_pk_add_f32 v[90:91], v[104:105], v[106:107]
	v_mul_f32_e32 v114, 0xbfb8aa3b, v77
	v_mul_f32_e32 v115, 0xbfb8aa3b, v79
	v_mul_f32_e32 v116, 0xbfb8aa3b, v80
	v_mul_f32_e32 v117, 0xbfb8aa3b, v82
	v_pk_fma_f32 v[46:47], v[64:65], v[64:65], v[46:47]
	v_exp_f32_e32 v134, v113
	v_lshlrev_b32_e32 v113, 16, v57
	v_and_b32_e32 v57, 0xffff0000, v57
	v_and_b32_e32 v56, 0xffff0000, v56
	v_pk_add_f32 v[90:91], v[90:91], v[90:91] op_sel_hi:[0,1]
	v_exp_f32_e32 v135, v114
	v_exp_f32_e32 v136, v115
	v_exp_f32_e32 v137, v116
	v_exp_f32_e32 v138, v117
	v_pk_add_f32 v[46:47], v[46:47], v[46:47] op_sel_hi:[0,1]
	v_pk_mul_f32 v[114:115], v[56:57], v[56:57]
	v_pk_mul_f32 v[116:117], v[112:113], v[112:113]
	v_add_f32_e32 v90, 1.0, v133
	v_mov_b32_e32 v72, v114
	v_mov_b32_e32 v46, v115
	v_mov_b32_e32 v48, v116
	v_rcp_f32_e32 v102, v90
	v_mov_b32_e32 v90, v117
	v_mov_b32_e32 v63, v2
	v_mov_b32_e32 v2, v1
	v_mul_f32_e32 v1, 0xbfb8aa3b, v44
	v_pk_add_f32 v[48:49], v[48:49], v[72:73]
	v_pk_add_f32 v[46:47], v[90:91], v[46:47]
	v_mov_b32_e32 v61, v6
	v_mov_b32_e32 v6, v5
	v_mul_f32_e32 v5, 0xbfb8aa3b, v74
	v_exp_f32_e32 v1, v1
	v_pk_add_f32 v[46:47], v[48:49], v[46:47]
	v_exp_f32_e32 v5, v5
	v_pk_add_f32 v[46:47], v[46:47], v[46:47] op_sel_hi:[0,1]
	v_mov_b32_e32 v88, v99
	v_mov_b32_e32 v46, v97
	v_pk_add_f32 v[46:47], v[88:89], v[46:47]
	v_add_f32_e32 v1, 1.0, v1
	v_pk_add_f32 v[46:47], v[50:51], v[46:47]
	v_add_f32_e32 v5, 1.0, v5
	v_rcp_f32_e32 v72, v1
	v_add_f32_e32 v1, v46, v47
	v_rcp_f32_e32 v98, v5
	ds_bpermute_b32 v5, v38, v1
	v_mul_f32_e32 v43, 0xbfb8aa3b, v45
	v_mul_f32_e32 v118, 0xbfb8aa3b, v81
	v_mul_f32_e32 v119, 0xbfb8aa3b, v83
	v_mul_f32_e32 v120, 0xbfb8aa3b, v84
	s_waitcnt lgkmcnt(0)
; __device__ __forceinline__ unsigned pk2(float lo, float hi) { return f2bf(lo) | (f2bf(hi) << 16); }
; __device__ __forceinline__ float siluf_(float x) { return x * __builtin_amdgcn_rcpf(1.0f + __expf(-x)); }
; __device__ __forceinline__ void gla_finalize(const Ctx& F) {
;     ...
;         ss += __shfl_xor(ss, 1); ss += __shfl_xor(ss, 2); ss += __shfl_xor(ss, 4); ss += __shfl_xor(ss, 8);
;         const float rstd = rsqrtf(ss * (1.0f / 512.0f) + EPS);
;         const u32x4* rp = (const u32x4*)(Y1 + (size_t)row * 6144 + 4096 + lane * 32); u32x4* cp = (u32x4*)(CAT + (size_t)row * 2048 + lane * 32);
; #pragma unroll
;         for (int i = 0; i < 4; ++i) { const u32x4 rv = rp[i]; const unsigned rr[4] = {rv.x, rv.y, rv.z, rv.w}; unsigned ov[4];
; #pragma unroll
;             for (int j = 0; j < 4; ++j) { const int e = i * 8 + j * 2; const float r0 = __uint_as_float(rr[j] << 16), r1 = __uint_as_float(rr[j] & 0xffff0000u);
;                 const float x0 = o[e >> 2][e & 3], x1 = o[(e + 1) >> 2][(e + 1) & 3];
;                 ov[j] = pk2(x0 * rstd * P.in[36][d0 + e] * siluf_(r0), x1 * rstd * P.in[36][d0 + e + 1] * siluf_(r1)); }
	v_add_f32_e32 v1, v1, v5
	ds_bpermute_b32 v5, v39, v1
	v_mul_f32_e32 v122, 0xbfb8aa3b, v85
	v_exp_f32_e32 v43, v43
	v_exp_f32_e32 v118, v118
	v_exp_f32_e32 v119, v119
	s_waitcnt lgkmcnt(0)
	v_add_f32_e32 v1, v1, v5
	ds_bpermute_b32 v5, v40, v1
	v_exp_f32_e32 v120, v120
	v_exp_f32_e32 v122, v122
	v_add_f32_e32 v43, 1.0, v43
	v_add_f32_e32 v103, 1.0, v134
	s_waitcnt lgkmcnt(0)
	v_add_f32_e32 v1, v1, v5
	ds_bpermute_b32 v5, v41, v1
	v_add_f32_e32 v105, 1.0, v135
	v_add_f32_e32 v106, 1.0, v136
	v_add_f32_e32 v107, 1.0, v137
	v_add_f32_e32 v109, 1.0, v118
	s_waitcnt lgkmcnt(0)
	v_add_f32_e32 v1, v1, v5
	v_fmamk_f32 v1, v1, 0x3b000000, v42
	v_mul_f32_e32 v5, 0x4b800000, v1
	v_cmp_gt_f32_e32 vcc, s9, v1
	v_add_f32_e32 v110, 1.0, v119
	v_add_f32_e32 v111, 1.0, v120
	v_cndmask_b32_e32 v1, v1, v5, vcc
	v_add_f32_e32 v115, 1.0, v122
	v_rsq_f32_e32 v1, v1
	v_rcp_f32_e32 v73, v43
	v_rcp_f32_e32 v104, v103
	v_rcp_f32_e32 v103, v105
	v_rcp_f32_e32 v105, v106
	v_rcp_f32_e32 v106, v107
	v_rcp_f32_e32 v107, v109
	v_rcp_f32_e32 v109, v110
	v_rcp_f32_e32 v110, v111
	v_rcp_f32_e32 v111, v115
	v_add_f32_e32 v96, 1.0, v132
	v_rcp_f32_e32 v99, v96
	v_mul_f32_e32 v5, 0x45800000, v1
	v_pk_mul_f32 v[44:45], v[72:73], v[44:45]
	v_pk_mul_f32 v[72:73], v[102:103], v[76:77]
	v_pk_mul_f32 v[76:77], v[106:107], v[80:81]
	v_pk_mul_f32 v[80:81], v[110:111], v[84:85]
	v_cndmask_b32_e32 v84, v1, v5, vcc
	v_pk_mul_f32 v[46:47], v[84:85], v[92:93] op_sel_hi:[0,1]
	v_pk_mul_f32 v[50:51], v[84:85], v[52:53] op_sel_hi:[0,1]
	v_pk_mul_f32 v[52:53], v[84:85], v[94:95] op_sel_hi:[0,1]
	v_pk_mul_f32 v[54:55], v[84:85], v[54:55] op_sel_hi:[0,1]
	v_pk_mul_f32 v[48:49], v[98:99], v[74:75]
	v_pk_mul_f32 v[74:75], v[104:105], v[78:79]
	v_pk_mul_f32 v[46:47], v[60:61], v[46:47]
	v_pk_mul_f32 v[6:7], v[6:7], v[50:51]
	v_pk_mul_f32 v[50:51], v[62:63], v[52:53]
	v_pk_mul_f32 v[2:3], v[2:3], v[54:55]
	v_pk_mul_f32 v[44:45], v[44:45], v[46:47]
	v_pk_mul_f32 v[6:7], v[48:49], v[6:7]
	v_pk_mul_f32 v[46:47], v[72:73], v[50:51]
	v_pk_mul_f32 v[2:3], v[74:75], v[2:3]
	v_bfe_u32 v43, v7, 16, 1
	v_bfe_u32 v1, v3, 16, 1
	v_bfe_u32 v5, v2, 16, 1
	v_bfe_u32 v49, v44, 16, 1
	v_bfe_u32 v50, v45, 16, 1
	v_bfe_u32 v51, v46, 16, 1
	v_bfe_u32 v52, v47, 16, 1
	v_bfe_u32 v48, v6, 16, 1
	v_add3_u32 v7, v7, v43, s22
	v_add3_u32 v2, v2, v5, s22
	v_add3_u32 v1, v3, v1, s22
	v_add3_u32 v3, v47, v52, s22
	v_add3_u32 v5, v46, v51, s22
	v_add3_u32 v43, v45, v50, s22
	v_add3_u32 v44, v44, v49, s22
	v_add3_u32 v6, v6, v48, s22
	v_lshrrev_b32_e32 v44, 16, v44
	v_lshrrev_b32_e32 v43, 16, v43
	v_lshrrev_b32_e32 v5, 16, v5
	v_lshrrev_b32_e32 v3, 16, v3
	v_and_or_b32 v47, v1, s3, v3
	v_and_or_b32 v46, v2, s3, v5
	v_and_or_b32 v45, v7, s3, v43
	v_and_or_b32 v44, v6, s3, v44
	global_store_dwordx4 v[22:23], v[44:47], off
	s_nop 1
	v_mov_b32_e32 v44, v168
	v_mov_b32_e32 v45, v169
	v_mov_b32_e32 v46, v170
	v_mov_b32_e32 v47, v171
	s_nop 0
	v_mov_b32_e32 v48, v172
	v_mov_b32_e32 v49, v173
	v_mov_b32_e32 v50, v174
	v_mov_b32_e32 v51, v175
	v_mul_f32_e32 v121, 0xbfb8aa3b, v86
	v_mul_f32_e32 v123, 0xbfb8aa3b, v87
	v_exp_f32_e32 v121, v121
	v_exp_f32_e32 v123, v123
	v_add_f32_e32 v108, 1.0, v138
	v_rcp_f32_e32 v108, v108
	v_add_f32_e32 v114, 1.0, v121
	v_add_f32_e32 v116, 1.0, v123
	v_rcp_f32_e32 v114, v114
	v_rcp_f32_e32 v115, v116
	v_pk_mul_f32 v[64:65], v[84:85], v[64:65] op_sel_hi:[0,1]
	v_pk_mul_f32 v[68:69], v[84:85], v[68:69] op_sel_hi:[0,1]
	v_pk_mul_f32 v[66:67], v[84:85], v[66:67] op_sel_hi:[0,1]
	v_pk_mul_f32 v[70:71], v[84:85], v[70:71] op_sel_hi:[0,1]
	v_pk_mul_f32 v[78:79], v[108:109], v[82:83]
	v_pk_mul_f32 v[82:83], v[114:115], v[86:87]
	v_mul_f32_e32 v124, 0xbfb8aa3b, v30
	v_mul_f32_e32 v125, 0xbfb8aa3b, v32
	v_mul_f32_e32 v126, 0xbfb8aa3b, v31
	v_mul_f32_e32 v127, 0xbfb8aa3b, v33
	v_mul_f32_e32 v128, 0xbfb8aa3b, v34
	v_mul_f32_e32 v129, 0xbfb8aa3b, v36
	v_mul_f32_e32 v130, 0xbfb8aa3b, v35
	v_mul_f32_e32 v131, 0xbfb8aa3b, v37
	v_exp_f32_e32 v124, v124
	v_exp_f32_e32 v125, v125
	v_exp_f32_e32 v126, v126
	v_exp_f32_e32 v127, v127
	v_exp_f32_e32 v128, v128
	v_exp_f32_e32 v129, v129
	v_exp_f32_e32 v130, v130
	v_exp_f32_e32 v131, v131
	v_add_f32_e32 v118, 1.0, v124
	v_add_f32_e32 v119, 1.0, v125
	v_add_f32_e32 v120, 1.0, v126
	v_add_f32_e32 v121, 1.0, v127
	v_add_f32_e32 v122, 1.0, v128
	v_add_f32_e32 v123, 1.0, v129
	v_add_f32_e32 v124, 1.0, v130
	v_rcp_f32_e32 v54, v123
	v_rcp_f32_e32 v53, v124
	v_lshlrev_b32_e32 v27, 16, v9
	v_lshlrev_b32_e32 v26, 16, v8
	v_pk_mul_f32 v[20:21], v[84:85], v[20:21] op_sel_hi:[0,1]
	v_pk_mul_f32 v[24:25], v[84:85], v[24:25] op_sel_hi:[0,1]
	v_mov_b32_e32 v2, v44
	v_mov_b32_e32 v3, v46
	v_mov_b32_e32 v6, v48
	v_mov_b32_e32 v7, v50
	v_mov_b32_e32 v46, v45
	v_mov_b32_e32 v50, v49
	v_pk_mul_f32 v[2:3], v[2:3], v[64:65]
	v_pk_mul_f32 v[6:7], v[6:7], v[68:69]
	v_pk_mul_f32 v[44:45], v[46:47], v[66:67]
	v_pk_mul_f32 v[46:47], v[50:51], v[70:71]
	v_pk_mul_f32 v[2:3], v[76:77], v[2:3]
	v_pk_mul_f32 v[6:7], v[80:81], v[6:7]
	v_pk_mul_f32 v[44:45], v[78:79], v[44:45]
	v_pk_mul_f32 v[46:47], v[82:83], v[46:47]
	v_bfe_u32 v49, v2, 16, 1
	v_bfe_u32 v50, v3, 16, 1
	v_bfe_u32 v51, v6, 16, 1
	v_bfe_u32 v52, v7, 16, 1
	v_bfe_u32 v1, v47, 16, 1
	v_bfe_u32 v5, v46, 16, 1
	v_bfe_u32 v43, v45, 16, 1
	v_bfe_u32 v48, v44, 16, 1
	v_add3_u32 v7, v7, v52, s22
	v_add3_u32 v6, v6, v51, s22
	v_add3_u32 v3, v3, v50, s22
; __device__ __forceinline__ unsigned pk2(float lo, float hi) { return f2bf(lo) | (f2bf(hi) << 16); }
; __device__ __forceinline__ float siluf_(float x) { return x * __builtin_amdgcn_rcpf(1.0f + __expf(-x)); }
; __device__ __forceinline__ void gla_finalize(const Ctx& F) {
;     ...
;         const u32x4* rp = (const u32x4*)(Y1 + (size_t)row * 6144 + 4096 + lane * 32); u32x4* cp = (u32x4*)(CAT + (size_t)row * 2048 + lane * 32);
; #pragma unroll
;         for (int i = 0; i < 4; ++i) { const u32x4 rv = rp[i]; const unsigned rr[4] = {rv.x, rv.y, rv.z, rv.w}; unsigned ov[4];
; #pragma unroll
;             for (int j = 0; j < 4; ++j) { const int e = i * 8 + j * 2; const float r0 = __uint_as_float(rr[j] << 16), r1 = __uint_as_float(rr[j] & 0xffff0000u);
;                 const float x0 = o[e >> 2][e & 3], x1 = o[(e + 1) >> 2][(e + 1) & 3];
;                 ov[j] = pk2(x0 * rstd * P.in[36][d0 + e] * siluf_(r0), x1 * rstd * P.in[36][d0 + e + 1] * siluf_(r1)); }
;             cp[i] = (u32x4){ov[0], ov[1], ov[2], ov[3]}; }
	v_add3_u32 v2, v2, v49, s22
	v_add3_u32 v44, v44, v48, s22
	v_add3_u32 v43, v45, v43, s22
	v_add3_u32 v5, v46, v5, s22
	v_add3_u32 v1, v47, v1, s22
	v_lshrrev_b32_e32 v2, 16, v2
	v_lshrrev_b32_e32 v3, 16, v3
	v_lshrrev_b32_e32 v6, 16, v6
	v_lshrrev_b32_e32 v7, 16, v7
	v_and_or_b32 v47, v1, s3, v7
	v_and_or_b32 v46, v5, s3, v6
	v_and_or_b32 v45, v43, s3, v3
	v_and_or_b32 v44, v44, s3, v2
	global_store_dwordx4 v[22:23], v[44:47], off offset:16
	s_nop 1
	v_mov_b32_e32 v44, v176
	v_mov_b32_e32 v45, v177
	v_mov_b32_e32 v46, v178
	v_mov_b32_e32 v47, v179
	s_nop 0
	v_mov_b32_e32 v48, v180
	v_mov_b32_e32 v49, v181
	v_mov_b32_e32 v50, v182
	v_mov_b32_e32 v51, v183
	v_add_f32_e32 v1, 1.0, v131
	v_rcp_f32_e32 v2, v118
	v_rcp_f32_e32 v6, v119
	v_rcp_f32_e32 v3, v120
	v_rcp_f32_e32 v7, v121
	v_rcp_f32_e32 v52, v122
	v_rcp_f32_e32 v55, v1
	v_pk_mul_f32 v[2:3], v[2:3], v[30:31]
	v_pk_mul_f32 v[6:7], v[6:7], v[32:33]
	v_pk_mul_f32 v[30:31], v[52:53], v[34:35]
	v_pk_mul_f32 v[32:33], v[54:55], v[36:37]
	v_pk_mul_f32 v[34:35], v[84:85], v[112:113] op_sel_hi:[0,1]
	v_pk_mul_f32 v[36:37], v[84:85], v[56:57] op_sel_hi:[0,1]
	v_pk_mul_f32 v[52:53], v[84:85], v[100:101] op_sel_hi:[0,1]
	v_pk_mul_f32 v[54:55], v[84:85], v[58:59] op_sel_hi:[0,1]
	v_mov_b32_e32 v56, v44
	v_mov_b32_e32 v57, v46
	v_mov_b32_e32 v46, v45
	v_mov_b32_e32 v44, v48
	v_mov_b32_e32 v45, v50
	v_mov_b32_e32 v50, v49
	v_pk_mul_f32 v[34:35], v[34:35], v[56:57]
	v_pk_mul_f32 v[44:45], v[52:53], v[44:45]
	v_pk_mul_f32 v[36:37], v[36:37], v[46:47]
	v_pk_mul_f32 v[46:47], v[54:55], v[50:51]
	v_pk_mul_f32 v[2:3], v[34:35], v[2:3]
	v_pk_mul_f32 v[30:31], v[30:31], v[44:45]
	v_pk_mul_f32 v[6:7], v[36:37], v[6:7]
	v_pk_mul_f32 v[32:33], v[32:33], v[46:47]
	v_bfe_u32 v36, v2, 16, 1
	v_bfe_u32 v37, v3, 16, 1
	v_bfe_u32 v43, v30, 16, 1
	v_bfe_u32 v44, v31, 16, 1
	v_bfe_u32 v1, v33, 16, 1
	v_bfe_u32 v5, v32, 16, 1
	v_bfe_u32 v34, v7, 16, 1
	v_bfe_u32 v35, v6, 16, 1
	v_add3_u32 v31, v31, v44, s22
	v_add3_u32 v30, v30, v43, s22
	v_add3_u32 v3, v3, v37, s22
	v_add3_u32 v2, v2, v36, s22
	v_add3_u32 v6, v6, v35, s22
	v_add3_u32 v7, v7, v34, s22
	v_add3_u32 v5, v32, v5, s22
	v_add3_u32 v1, v33, v1, s22
	v_lshrrev_b32_e32 v2, 16, v2
	v_lshrrev_b32_e32 v3, 16, v3
	v_lshrrev_b32_e32 v30, 16, v30
	v_lshrrev_b32_e32 v31, 16, v31
	v_and_or_b32 v33, v1, s3, v31
	v_and_or_b32 v32, v5, s3, v30
	v_and_or_b32 v31, v7, s3, v3
	v_and_or_b32 v30, v6, s3, v2
	global_store_dwordx4 v[22:23], v[30:33], off offset:32
	s_nop 1
	v_mov_b32_e32 v30, v184
	v_mov_b32_e32 v31, v185
	v_mov_b32_e32 v32, v186
	v_mov_b32_e32 v33, v187
	s_nop 0
	v_mov_b32_e32 v34, v188
	v_mov_b32_e32 v35, v189
	v_mov_b32_e32 v36, v190
	v_mov_b32_e32 v37, v191
	v_and_b32_e32 v3, 0xffff0000, v9
	v_and_b32_e32 v2, 0xffff0000, v8
	v_lshlrev_b32_e32 v7, 16, v11
	v_lshlrev_b32_e32 v6, 16, v10
	v_and_b32_e32 v9, 0xffff0000, v11
	v_and_b32_e32 v8, 0xffff0000, v10
	v_mul_f32_e32 v10, 0xbfb8aa3b, v26
	v_mul_f32_e32 v11, 0xbfb8aa3b, v2
	v_mov_b32_e32 v5, v28
	v_mul_f32_e32 v28, 0xbfb8aa3b, v27
	v_mov_b32_e32 v1, v29
	v_mul_f32_e32 v29, 0xbfb8aa3b, v3
	v_mul_f32_e32 v43, 0xbfb8aa3b, v6
	v_mul_f32_e32 v45, 0xbfb8aa3b, v7
	v_exp_f32_e32 v10, v10
	v_exp_f32_e32 v11, v11
	v_exp_f32_e32 v28, v28
	v_exp_f32_e32 v29, v29
	v_mul_f32_e32 v44, 0xbfb8aa3b, v8
	v_mul_f32_e32 v46, 0xbfb8aa3b, v9
	v_exp_f32_e32 v43, v43
	v_exp_f32_e32 v45, v45
	v_exp_f32_e32 v44, v44
	v_exp_f32_e32 v46, v46
	v_add_f32_e32 v10, 1.0, v10
	v_add_f32_e32 v11, 1.0, v11
	v_add_f32_e32 v47, 1.0, v28
	v_add_f32_e32 v29, 1.0, v29
	v_add_f32_e32 v43, 1.0, v43
	v_add_f32_e32 v45, 1.0, v45
	v_rcp_f32_e32 v10, v10
	v_rcp_f32_e32 v28, v11
	v_rcp_f32_e32 v11, v47
	v_rcp_f32_e32 v29, v29
	v_add_f32_e32 v48, 1.0, v44
	v_add_f32_e32 v49, 1.0, v46
	v_rcp_f32_e32 v44, v43
	v_rcp_f32_e32 v45, v45
	v_rcp_f32_e32 v46, v48
	v_rcp_f32_e32 v47, v49
	v_pk_mul_f32 v[10:11], v[10:11], v[26:27]
	v_pk_mul_f32 v[2:3], v[28:29], v[2:3]
	v_pk_mul_f32 v[4:5], v[84:85], v[4:5] op_sel_hi:[0,1]
	v_pk_mul_f32 v[0:1], v[84:85], v[0:1] op_sel_hi:[0,1]
	v_pk_mul_f32 v[6:7], v[44:45], v[6:7]
	v_pk_mul_f32 v[8:9], v[46:47], v[8:9]
	v_mov_b32_e32 v26, v30
	v_mov_b32_e32 v27, v32
	v_mov_b32_e32 v32, v31
	v_mov_b32_e32 v28, v34
	v_mov_b32_e32 v29, v36
	v_mov_b32_e32 v36, v35
	v_pk_mul_f32 v[4:5], v[4:5], v[26:27]
	v_pk_mul_f32 v[0:1], v[0:1], v[32:33]
	v_pk_mul_f32 v[20:21], v[20:21], v[28:29]
	v_pk_mul_f32 v[24:25], v[24:25], v[36:37]
	v_pk_mul_f32 v[4:5], v[4:5], v[10:11]
	v_pk_mul_f32 v[0:1], v[0:1], v[2:3]
	v_pk_mul_f32 v[2:3], v[6:7], v[20:21]
	v_pk_mul_f32 v[6:7], v[8:9], v[24:25]
	v_bfe_u32 v20, v4, 16, 1
	v_bfe_u32 v21, v5, 16, 1
	v_bfe_u32 v24, v2, 16, 1
	v_bfe_u32 v25, v3, 16, 1
	v_bfe_u32 v8, v7, 16, 1
	v_bfe_u32 v9, v6, 16, 1
	v_bfe_u32 v10, v1, 16, 1
	v_bfe_u32 v11, v0, 16, 1
	v_add3_u32 v3, v3, v25, s22
	v_add3_u32 v2, v2, v24, s22
	v_add3_u32 v5, v5, v21, s22
	v_add3_u32 v4, v4, v20, s22
	v_add3_u32 v0, v0, v11, s22
	v_add3_u32 v1, v1, v10, s22
	v_add3_u32 v6, v6, v9, s22
	v_add3_u32 v7, v7, v8, s22
	v_lshrrev_b32_e32 v4, 16, v4
	v_lshrrev_b32_e32 v5, 16, v5
	v_lshrrev_b32_e32 v2, 16, v2
	v_lshrrev_b32_e32 v3, 16, v3
	v_and_or_b32 v3, v7, s3, v3
	v_and_or_b32 v2, v6, s3, v2
	v_and_or_b32 v1, v1, s3, v5
	v_and_or_b32 v0, v0, s3, v4
	global_store_dwordx4 v[22:23], v[0:3], off offset:48
	s_cbranch_scc1 .LBB0_1904
